# attention: K fragments of keys 32..63 held in spare registers for both query groups (4 fewer LDS b128 reads per K/V tile)
# speedup vs baseline: 1.0007x; 1.0007x over previous
.LBB0_452:
	s_setprio 2
	v_add3_u32 v197, s54, v190, v215
	ds_read_b128 v[68:71], v197
	ds_read_b128 v[72:75], v197 offset:32
	ds_read_b128 v[76:79], v197 offset:64
	ds_read_b128 v[80:83], v197 offset:96
	ds_read_b128 v[222:225], v197 offset:4608
	ds_read_b128 v[226:229], v197 offset:4640
	ds_read_b128 v[230:233], v197 offset:4672
	ds_read_b128 v[234:237], v197 offset:4704
	global_load_dwordx4 v[136:139], v246, s[60:61]
	global_load_dwordx4 v[140:143], v246, s[62:63]
	s_waitcnt lgkmcnt(7)
	v_mfma_f32_32x32x16_bf16 v[100:115], v[68:71], v[132:135], 0
	global_load_dwordx4 v[176:179], v247, s[64:65]
	global_load_dwordx4 v[144:147], v247, s[66:67]
	s_waitcnt lgkmcnt(6)
	v_mfma_f32_32x32x16_bf16 v[100:115], v[72:75], v[156:159], v[100:115]
	v_add3_u32 v210, s54, v188, v65
	v_add_u32_e32 v211, 0x3000, v210
	s_waitcnt lgkmcnt(5)
	v_mfma_f32_32x32x16_bf16 v[100:115], v[76:79], v[152:155], v[100:115]
	v_add_u32_e32 v210, 0x2000, v210
	s_waitcnt lgkmcnt(4)
	v_mfma_f32_32x32x16_bf16 v[100:115], v[80:83], v[148:151], v[100:115]
	s_waitcnt lgkmcnt(3)
	v_mfma_f32_32x32x16_bf16 v[116:131], v[222:225], v[132:135], 0
	s_waitcnt lgkmcnt(2)
	v_mfma_f32_32x32x16_bf16 v[116:131], v[226:229], v[156:159], v[116:131]
	s_waitcnt lgkmcnt(1)
	v_mfma_f32_32x32x16_bf16 v[116:131], v[230:233], v[152:155], v[116:131]
	s_waitcnt lgkmcnt(0)
	v_mfma_f32_32x32x16_bf16 v[116:131], v[234:237], v[148:151], v[116:131]
	s_nop 2
	v_mfma_f32_32x32x16_bf16 v[84:99], v[68:71], v[172:175], 0
	v_max3_f32 v67, v100, v101, v102
	v_max3_f32 v67, v67, v103, v104
	v_mfma_f32_32x32x16_bf16 v[84:99], v[72:75], v[168:171], v[84:99]
	v_max3_f32 v67, v67, v105, v106
	v_max3_f32 v67, v67, v107, v108
	v_mfma_f32_32x32x16_bf16 v[84:99], v[76:79], v[164:167], v[84:99]
	v_max3_f32 v67, v67, v109, v110
	v_max3_f32 v67, v67, v111, v112
	v_mfma_f32_32x32x16_bf16 v[84:99], v[80:83], v[160:163], v[84:99]
	v_max3_f32 v67, v67, v113, v114
	v_max_f32_e32 v67, v67, v115
	v_mfma_f32_32x32x16_bf16 v[68:83], v[222:225], v[172:175], 0
	v_max3_f32 v182, v116, v117, v118
	v_max3_f32 v182, v182, v119, v120
	v_max3_f32 v182, v182, v121, v122
	v_max3_f32 v182, v182, v123, v124
	v_mfma_f32_32x32x16_bf16 v[68:83], v[226:229], v[168:171], v[68:83]
	v_max3_f32 v182, v182, v125, v126
	v_max3_f32 v182, v182, v127, v128
	v_max3_f32 v182, v182, v129, v130
	v_max_f32_e32 v182, v182, v131
	v_max_f32_e32 v67, v67, v182
	ds_bpermute_b32 v182, v191, v67
	v_mfma_f32_32x32x16_bf16 v[68:83], v[230:233], v[164:167], v[68:83]
	v_mfma_f32_32x32x16_bf16 v[68:83], v[234:237], v[160:163], v[68:83]
	ds_read2_b64 v[206:209], v210 offset0:128 offset1:130
	ds_read2_b64 v[218:221], v211 offset0:160 offset1:162
	s_waitcnt lgkmcnt(2)
	v_max3_f32 v66, v216, v67, v182
	v_cmp_gt_f32_e32 vcc, v66, v216
	s_cbranch_vccz .Lattn_keep0
	v_sub_f32_e32 v182, v216, v66
	v_exp_f32_e32 v182, v182
	s_nop 0
	v_pk_mul_f32 v[48:49], v[48:49], v[182:183] op_sel_hi:[1,0]
	v_pk_mul_f32 v[50:51], v[50:51], v[182:183] op_sel_hi:[1,0]
	v_pk_mul_f32 v[52:53], v[52:53], v[182:183] op_sel_hi:[1,0]
	v_pk_mul_f32 v[54:55], v[54:55], v[182:183] op_sel_hi:[1,0]
	v_pk_mul_f32 v[56:57], v[56:57], v[182:183] op_sel_hi:[1,0]
	v_pk_mul_f32 v[58:59], v[58:59], v[182:183] op_sel_hi:[1,0]
	v_pk_mul_f32 v[60:61], v[60:61], v[182:183] op_sel_hi:[1,0]
	v_pk_mul_f32 v[62:63], v[62:63], v[182:183] op_sel_hi:[1,0]
	v_pk_mul_f32 v[16:17], v[16:17], v[182:183] op_sel_hi:[1,0]
	v_pk_mul_f32 v[18:19], v[18:19], v[182:183] op_sel_hi:[1,0]
	v_pk_mul_f32 v[20:21], v[20:21], v[182:183] op_sel_hi:[1,0]
	v_pk_mul_f32 v[22:23], v[22:23], v[182:183] op_sel_hi:[1,0]
	v_pk_mul_f32 v[24:25], v[24:25], v[182:183] op_sel_hi:[1,0]
	v_pk_mul_f32 v[26:27], v[26:27], v[182:183] op_sel_hi:[1,0]
	v_pk_mul_f32 v[28:29], v[28:29], v[182:183] op_sel_hi:[1,0]
	v_pk_mul_f32 v[30:31], v[30:31], v[182:183] op_sel_hi:[1,0]
	v_mul_f32_e32 v194, v194, v182
	v_mov_b32_e32 v216, v66
